# attention commit: next-unit queue draw issued behind the bias loads (overlaps K/V waits), id published before the commit barrier, one barrier fewer
# speedup vs baseline: 1.0085x; 1.0079x over previous
; #define PROBE_BEGIN(id) unsigned long long pb_t0_##id = 0; if (PROBE_SEC == (id)) pb_t0_##id = __builtin_amdgcn_s_memrealtime();
; #define PROBE_END(id) if (PROBE_SEC == (id)) { const unsigned long long pb_t1_ = __builtin_amdgcn_s_memrealtime(), pb_dt_ = pb_t1_ - pb_t0_##id; while (__builtin_amdgcn_s_memrealtime() - pb_t1_ < pb_dt_) __builtin_amdgcn_s_sleep(4); }
; #define LAS __attribute__((address_space(3)))
; __device__ __forceinline__ void attn_commit(Frame& F, int id, const KvRegs& R) {
;     LAS unsigned char* lds = F.lds; const int tid = F.tid, kvh = id & 1;
;     PROBE_BEGIN(3)
; #pragma unroll
;     for (int i = 0; i < 6; ++i) { const int p = tid + 512 * i, row = p >> 3, pc = p & 7; *(LAS v4u*)(lds + OFF_K + row * KROW + pc * 16) = R.k[i]; }
; #pragma unroll
;     for (int i = 0; i < 6; ++i) { const int p = tid + 512 * i, d = p / 48, pc = p - d * 48;
;         *(LAS v2u*)(lds + OFF_V + d * VROW + pc * 16) = (v2u){R.v[i].x, R.v[i].y}; *(LAS v2u*)(lds + OFF_V + d * VROW + pc * 16 + 8) = (v2u){R.v[i].z, R.v[i].w}; }
;     LAS f32x4* BT4 = (LAS f32x4*)(lds + OFF_B);
;     {   const f32x4* src = (const f32x4*)(F.ws + WS_BT4) + kvh * 4 * NBT;
; #pragma unroll
;         for (int i = 0; i < 3; ++i) BT4[tid + 512 * i] = src[tid + 512 * i]; }
;     __syncthreads();
;     PROBE_END(3)
; }
; __device__ __forceinline__ void p2_mix(Frame& F, int slot) {
;     ...
;     while (id < NU) {
;         att::attn_commit(F, base + id, R);
;         if (F.tid == 0) F.MISC[16] = __hip_atomic_fetch_add(F.ctl + CW_ATTQ + 64 * F.dom, 1u, RLX_AGENT);
;         __syncthreads();
;         const int nid = (int)F.MISC[16];
;         if (nid < NU) att::attn_issue(F, base + nid, R);
.LBB0_545:
	s_lshl_b32 s2, s33, 2
	s_and_b32 s45, s2, 4
	s_add_i32 s54, s27, s45
	s_lshl_b32 s54, s54, 2
	s_load_dword s55, s[20:21], s54
	s_mul_i32 s2, s45, 0x1800
	s_add_u32 s2, s25, s2
	s_addc_u32 s3, s26, 0
	v_mov_b32_e32 v201, v2
	v_lshl_add_u64 v[8:9], s[2:3], 0, v[200:201]
	v_add_co_u32_e32 v8, vcc, 0x2000, v8
	global_load_dwordx4 v[4:7], v200, s[2:3]
	s_nop 0
	v_addc_co_u32_e32 v9, vcc, 0, v9, vcc
	global_load_dwordx4 v[8:11], v[8:9], off
	s_nop 0
	global_load_dwordx4 v[12:15], v242, s[2:3]
	v_mov_b32_e32 v250, 1
	s_cmp_eq_u64 s[0:1], 0
	s_cbranch_scc1 .Lqd_other
	s_mov_b64 s[48:49], exec
	s_mov_b64 exec, s[0:1]
	global_atomic_add v250, v2, v250, s[16:17] sc0
	s_mov_b64 exec, s[48:49]
	s_branch .Lqd_join
.Lqd_other:
	global_load_dword v250, v2, s[2:3]
.Lqd_join:
	s_waitcnt vmcnt(5)
	ds_write_b128 v230, v[114:117]
	ds_write_b128 v231, v[118:121]
	s_waitcnt vmcnt(4)
	ds_write_b128 v232, v[126:129]
	ds_write_b128 v233, v[122:125]
	ds_write_b128 v234, v[130:133]
	ds_write_b128 v235, v[134:137]
	ds_write2_b64 v236, v[138:139], v[140:141] offset1:1
	ds_write2_b64 v237, v[142:143], v[144:145] offset1:1
	ds_write2_b64 v238, v[146:147], v[148:149] offset1:1
	ds_write2_b64 v239, v[150:151], v[152:153] offset1:1
	ds_write2_b64 v240, v[154:155], v[156:157] offset1:1
	ds_write2_b64 v241, v[158:159], v[160:161] offset1:1
	s_waitcnt vmcnt(3)
	ds_write_b128 v218, v[4:7]
	s_waitcnt vmcnt(2)
	ds_write_b128 v219, v[8:11]
	s_waitcnt vmcnt(1)
	ds_write_b128 v220, v[12:15]
	s_and_saveexec_b64 s[2:3], s[0:1]
	s_waitcnt vmcnt(0)
	v_mov_b32_e32 v3, s41
	ds_write_b32 v3, v250
	s_or_b64 exec, exec, s[2:3]
	v_mov_b32_e32 v3, s41
	s_waitcnt lgkmcnt(0)
	s_barrier
	ds_read_b32 v3, v3
	s_waitcnt lgkmcnt(0)
	v_cmp_lt_i32_e64 s[2:3], s42, v3
	v_readfirstlane_b32 s44, v3
	s_and_b64 vcc, exec, s[2:3]
	s_cbranch_vccnz .LBB0_574
	s_add_i32 s4, s44, s11
	s_ashr_i32 s23, s4, 5
	s_lshl_b32 s4, s4, 6
	s_and_b32 s22, s4, 0x780
	s_and_b32 s46, s4, 64
	s_addk_i32 s22, 0xff80
	s_lshl_b32 s47, s23, 11
	s_lshl_b32 s14, s46, 1
	s_cmpk_gt_u32 s22, 0x7ff
	v_lshl_add_u64 v[6:7], v[194:195], 0, s[14:15]
	s_cbranch_scc1 .LBB0_552
	v_or_b32_e32 v3, s22, v1
	v_or_b32_e32 v4, s47, v3
	v_ashrrev_i32_e32 v5, 31, v4
	v_lshlrev_b64 v[4:5], 8, v[4:5]
	v_lshl_add_u64 v[4:5], v[6:7], 0, v[4:5]
	global_load_dwordx4 v[114:117], v[4:5], off
	s_branch .LBB0_553
